# KV up-projection epilogue (key half): per-row scales requested before the K loop, eight serialized load+drain steps removed
# speedup vs baseline: 1.0069x; 1.0069x over previous
; template <class Epi, class Sched, bool ALIGN_EPI = false, bool SP2 = false>
; __device__ __forceinline__ void gemm_phase(LAS unsigned char* lds, const Gemm g, const Sched S, const Epi E) {
;     ...
; #pragma unroll
;         for (int a = 0; a < 2; ++a)
; #pragma unroll
;             for (int b = 0; b < 2; ++b)
; #pragma unroll
;                 for (int m = 0; m < 4; ++m)
; #pragma unroll
;                     for (int n = 0; n < 2; ++n) acc[a][b][m][n] = (f32x4){0.f, 0.f, 0.f, 0.f};
.LBB0_1436:
	s_ashr_i32 s57, s56, 31
	s_lshl_b64 s[12:13], s[56:57], 17
	s_add_u32 s64, s52, s12
	s_addc_u32 s65, s53, s13
	s_and_b64 s[8:9], s[8:9], exec
	v_mov_b32_e32 v0, 0
	s_cselect_b32 s57, s65, s67
	s_cselect_b32 s89, s64, s66
	s_mov_b64 s[72:73], 0
	s_mov_b64 s[8:9], -1
	s_mov_b64 s[70:71], 0
	v_mov_b32_e32 v1, v0
	v_mov_b32_e32 v2, v0
	v_mov_b32_e32 v3, v0
	v_mov_b32_e32 v4, v0
	v_mov_b32_e32 v5, v0
	v_mov_b32_e32 v6, v0
	v_mov_b32_e32 v7, v0
	s_waitcnt vmcnt(0)
	v_mov_b32_e32 v16, v0
	v_mov_b32_e32 v17, v0
	v_mov_b32_e32 v18, v0
	v_mov_b32_e32 v19, v0
	v_mov_b32_e32 v20, v0
	v_mov_b32_e32 v21, v0
	v_mov_b32_e32 v22, v0
	v_mov_b32_e32 v23, v0
	v_mov_b32_e32 v32, v0
	v_mov_b32_e32 v33, v0
	v_mov_b32_e32 v34, v0
	v_mov_b32_e32 v35, v0
	v_mov_b32_e32 v36, v0
	v_mov_b32_e32 v37, v0
	v_mov_b32_e32 v38, v0
	v_mov_b32_e32 v39, v0
	v_mov_b32_e32 v48, v0
	v_mov_b32_e32 v49, v0
	v_mov_b32_e32 v50, v0
	v_mov_b32_e32 v51, v0
	v_mov_b32_e32 v52, v0
	v_mov_b32_e32 v53, v0
	v_mov_b32_e32 v54, v0
	v_mov_b32_e32 v55, v0
	v_mov_b32_e32 v8, v0
	v_mov_b32_e32 v9, v0
	v_mov_b32_e32 v10, v0
	v_mov_b32_e32 v11, v0
	v_mov_b32_e32 v12, v0
	v_mov_b32_e32 v13, v0
	v_mov_b32_e32 v14, v0
	v_mov_b32_e32 v15, v0
	v_mov_b32_e32 v24, v0
	v_mov_b32_e32 v25, v0
	v_mov_b32_e32 v26, v0
	v_mov_b32_e32 v27, v0
	v_mov_b32_e32 v28, v0
	v_mov_b32_e32 v29, v0
	v_mov_b32_e32 v30, v0
	v_mov_b32_e32 v31, v0
	v_mov_b32_e32 v40, v0
	v_mov_b32_e32 v41, v0
	v_mov_b32_e32 v42, v0
	v_mov_b32_e32 v43, v0
	v_mov_b32_e32 v44, v0
	v_mov_b32_e32 v45, v0
	v_mov_b32_e32 v46, v0
	v_mov_b32_e32 v47, v0
	v_mov_b32_e32 v56, v0
	v_mov_b32_e32 v57, v0
	v_mov_b32_e32 v58, v0
	v_mov_b32_e32 v59, v0
	v_mov_b32_e32 v60, v0
	v_mov_b32_e32 v61, v0
	v_mov_b32_e32 v62, v0
	v_mov_b32_e32 v63, v0
	v_mov_b32_e32 v64, v0
	v_mov_b32_e32 v65, v0
	v_mov_b32_e32 v66, v0
	v_mov_b32_e32 v67, v0
	v_mov_b32_e32 v68, v0
	v_mov_b32_e32 v69, v0
	v_mov_b32_e32 v70, v0
	v_mov_b32_e32 v71, v0
	v_mov_b32_e32 v80, v0
	v_mov_b32_e32 v81, v0
	v_mov_b32_e32 v82, v0
	v_mov_b32_e32 v83, v0
	v_mov_b32_e32 v84, v0
	v_mov_b32_e32 v85, v0
	v_mov_b32_e32 v86, v0
	v_mov_b32_e32 v87, v0
	v_mov_b32_e32 v96, v0
	v_mov_b32_e32 v97, v0
	v_mov_b32_e32 v98, v0
	v_mov_b32_e32 v99, v0
	v_mov_b32_e32 v100, v0
	v_mov_b32_e32 v101, v0
	v_mov_b32_e32 v102, v0
	v_mov_b32_e32 v103, v0
	v_mov_b32_e32 v112, v0
	v_mov_b32_e32 v113, v0
	v_mov_b32_e32 v114, v0
	v_mov_b32_e32 v115, v0
	v_mov_b32_e32 v116, v0
	v_mov_b32_e32 v117, v0
	v_mov_b32_e32 v118, v0
	v_mov_b32_e32 v119, v0
	v_mov_b32_e32 v72, v0
	v_mov_b32_e32 v73, v0
	v_mov_b32_e32 v74, v0
	v_mov_b32_e32 v75, v0
	v_mov_b32_e32 v76, v0
	v_mov_b32_e32 v77, v0
	v_mov_b32_e32 v78, v0
	v_mov_b32_e32 v79, v0
	v_mov_b32_e32 v88, v0
	v_mov_b32_e32 v89, v0
	v_mov_b32_e32 v90, v0
	v_mov_b32_e32 v91, v0
	v_mov_b32_e32 v92, v0
	v_mov_b32_e32 v93, v0
	v_mov_b32_e32 v94, v0
	v_mov_b32_e32 v95, v0
	v_mov_b32_e32 v104, v0
	v_mov_b32_e32 v105, v0
	v_mov_b32_e32 v106, v0
	v_mov_b32_e32 v107, v0
	v_mov_b32_e32 v108, v0
	v_mov_b32_e32 v109, v0
	v_mov_b32_e32 v110, v0
	v_mov_b32_e32 v111, v0
	v_mov_b32_e32 v120, v0
	v_mov_b32_e32 v121, v0
	v_mov_b32_e32 v122, v0
	v_mov_b32_e32 v123, v0
	v_mov_b32_e32 v124, v0
	v_mov_b32_e32 v125, v0
	v_mov_b32_e32 v126, v0
	v_mov_b32_e32 v127, v0
	s_lshl_b32 s100, s10, 8
	s_add_i32 s100, s100, s33
	v_or_b32_e32 v252, s100, v139
	v_lshlrev_b32_e32 v252, 1, v252
	v_ashrrev_i32_e32 v253, 31, v252
	v_lshl_add_u64 v[252:253], v[252:253], 2, s[62:63]
	global_load_dword v244, v[252:253], off offset:4
	global_load_dword v245, v[252:253], off offset:132
	global_load_dword v246, v[252:253], off offset:260
	global_load_dword v247, v[252:253], off offset:388
	global_load_dword v248, v[252:253], off offset:1028
	global_load_dword v249, v[252:253], off offset:1156
	global_load_dword v250, v[252:253], off offset:1284
	global_load_dword v251, v[252:253], off offset:1412

.LBB0_1444:
	v_lshl_add_u64 v[148:149], v[148:149], 2, s[62:63]
	v_mov_b32_e32 v150, v244
	v_lshl_or_b32 v148, s88, 8, v157
	v_ashrrev_i32_e32 v147, 31, v146
	v_or_b32_e32 v152, 16, v146
	v_ashrrev_i32_e32 v149, 31, v148
	v_lshlrev_b64 v[154:155], 11, v[146:147]
	v_lshlrev_b32_e32 v164, 1, v152
	v_lshl_add_u64 v[154:155], s[48:49], 0, v[154:155]
	v_lshlrev_b64 v[148:149], 1, v[148:149]
	v_ashrrev_i32_e32 v165, 31, v164
	v_lshl_add_u64 v[154:155], v[154:155], 0, v[148:149]
	v_lshl_add_u64 v[164:165], v[164:165], 2, s[62:63]
	v_ashrrev_i32_e32 v153, 31, v152
	v_pk_mul_f32 v[126:127], v[126:127], v[150:151] op_sel_hi:[1,0]
	v_pk_mul_f32 v[124:125], v[124:125], v[150:151] op_sel_hi:[1,0]
	v_pk_mul_f32 v[122:123], v[122:123], v[150:151] op_sel_hi:[1,0]
	v_pk_mul_f32 v[120:121], v[120:121], v[150:151] op_sel_hi:[1,0]
	v_pk_mul_f32 v[118:119], v[118:119], v[150:151] op_sel_hi:[1,0]
	v_pk_mul_f32 v[116:117], v[116:117], v[150:151] op_sel_hi:[1,0]
	v_pk_mul_f32 v[166:167], v[114:115], v[150:151] op_sel_hi:[1,0]
	v_pk_mul_f32 v[150:151], v[112:113], v[150:151] op_sel_hi:[1,0]
	v_cvt_pk_bf16_f32 v112, v124, v125
	v_cvt_pk_bf16_f32 v113, v126, v127
	v_cvt_pk_bf16_f32 v114, v120, v121
	v_cvt_pk_bf16_f32 v115, v122, v123
	v_cvt_pk_bf16_f32 v116, v116, v117
	v_cvt_pk_bf16_f32 v117, v118, v119
	v_cvt_pk_bf16_f32 v118, v150, v151
	v_cvt_pk_bf16_f32 v119, v166, v167
	global_store_dwordx4 v[154:155], v[112:115], off
	global_store_dwordx4 v[154:155], v[116:119], off offset:256
	s_nop 1
	v_mov_b32_e32 v112, v245
	v_or_b32_e32 v114, 32, v146
	v_lshlrev_b64 v[118:119], 11, v[152:153]
	v_lshlrev_b32_e32 v116, 1, v114
	v_lshl_add_u64 v[118:119], s[48:49], 0, v[118:119]
	v_ashrrev_i32_e32 v117, 31, v116
	v_lshl_add_u64 v[118:119], v[118:119], 0, v[148:149]
	v_lshl_add_u64 v[116:117], v[116:117], 2, s[62:63]
	v_ashrrev_i32_e32 v115, 31, v114
	v_pk_mul_f32 v[110:111], v[110:111], v[112:113] op_sel_hi:[1,0]
	v_pk_mul_f32 v[108:109], v[108:109], v[112:113] op_sel_hi:[1,0]
	v_pk_mul_f32 v[106:107], v[106:107], v[112:113] op_sel_hi:[1,0]
	v_pk_mul_f32 v[104:105], v[104:105], v[112:113] op_sel_hi:[1,0]
	v_pk_mul_f32 v[102:103], v[102:103], v[112:113] op_sel_hi:[1,0]
	v_pk_mul_f32 v[100:101], v[100:101], v[112:113] op_sel_hi:[1,0]
	v_pk_mul_f32 v[120:121], v[98:99], v[112:113] op_sel_hi:[1,0]
	v_pk_mul_f32 v[112:113], v[96:97], v[112:113] op_sel_hi:[1,0]
	v_cvt_pk_bf16_f32 v96, v108, v109
	v_cvt_pk_bf16_f32 v97, v110, v111
	v_cvt_pk_bf16_f32 v98, v104, v105
	v_cvt_pk_bf16_f32 v99, v106, v107
	v_cvt_pk_bf16_f32 v100, v100, v101
	v_cvt_pk_bf16_f32 v101, v102, v103
	v_cvt_pk_bf16_f32 v102, v112, v113
	v_cvt_pk_bf16_f32 v103, v120, v121
	global_store_dwordx4 v[118:119], v[96:99], off
	global_store_dwordx4 v[118:119], v[100:103], off offset:256
	s_nop 1
	v_mov_b32_e32 v96, v246
	v_or_b32_e32 v98, 48, v146
	v_lshlrev_b64 v[102:103], 11, v[114:115]
	v_lshlrev_b32_e32 v100, 1, v98
	v_lshl_add_u64 v[102:103], s[48:49], 0, v[102:103]
	v_ashrrev_i32_e32 v101, 31, v100
	v_lshl_add_u64 v[102:103], v[102:103], 0, v[148:149]
	v_lshl_add_u64 v[100:101], v[100:101], 2, s[62:63]
	v_ashrrev_i32_e32 v99, 31, v98
	v_pk_mul_f32 v[94:95], v[94:95], v[96:97] op_sel_hi:[1,0]
	v_pk_mul_f32 v[92:93], v[92:93], v[96:97] op_sel_hi:[1,0]
	v_pk_mul_f32 v[90:91], v[90:91], v[96:97] op_sel_hi:[1,0]
	v_pk_mul_f32 v[88:89], v[88:89], v[96:97] op_sel_hi:[1,0]
	v_pk_mul_f32 v[86:87], v[86:87], v[96:97] op_sel_hi:[1,0]
	v_pk_mul_f32 v[84:85], v[84:85], v[96:97] op_sel_hi:[1,0]
	v_pk_mul_f32 v[104:105], v[82:83], v[96:97] op_sel_hi:[1,0]
	v_pk_mul_f32 v[96:97], v[80:81], v[96:97] op_sel_hi:[1,0]
	v_cvt_pk_bf16_f32 v80, v92, v93
	v_cvt_pk_bf16_f32 v81, v94, v95
	v_cvt_pk_bf16_f32 v82, v88, v89
	v_cvt_pk_bf16_f32 v83, v90, v91
	v_cvt_pk_bf16_f32 v84, v84, v85
	v_cvt_pk_bf16_f32 v85, v86, v87
	v_cvt_pk_bf16_f32 v86, v96, v97
	v_cvt_pk_bf16_f32 v87, v104, v105
	global_store_dwordx4 v[102:103], v[80:83], off
	global_store_dwordx4 v[102:103], v[84:87], off offset:256
	s_nop 1
	v_mov_b32_e32 v80, v247
	v_add_u32_e32 v82, 0x80, v146
	v_lshlrev_b64 v[86:87], 11, v[98:99]
	v_lshlrev_b32_e32 v84, 1, v82
	v_lshl_add_u64 v[86:87], s[48:49], 0, v[86:87]
	v_ashrrev_i32_e32 v85, 31, v84
	v_lshl_add_u64 v[86:87], v[86:87], 0, v[148:149]
	v_lshl_add_u64 v[84:85], v[84:85], 2, s[62:63]
	v_ashrrev_i32_e32 v83, 31, v82
	v_pk_mul_f32 v[78:79], v[78:79], v[80:81] op_sel_hi:[1,0]
	v_pk_mul_f32 v[76:77], v[76:77], v[80:81] op_sel_hi:[1,0]
	v_pk_mul_f32 v[74:75], v[74:75], v[80:81] op_sel_hi:[1,0]
	v_pk_mul_f32 v[72:73], v[72:73], v[80:81] op_sel_hi:[1,0]
	v_pk_mul_f32 v[70:71], v[70:71], v[80:81] op_sel_hi:[1,0]
	v_pk_mul_f32 v[68:69], v[68:69], v[80:81] op_sel_hi:[1,0]
	v_pk_mul_f32 v[88:89], v[66:67], v[80:81] op_sel_hi:[1,0]
	v_pk_mul_f32 v[80:81], v[64:65], v[80:81] op_sel_hi:[1,0]
	v_cvt_pk_bf16_f32 v64, v76, v77
	v_cvt_pk_bf16_f32 v65, v78, v79
	v_cvt_pk_bf16_f32 v66, v72, v73
	v_cvt_pk_bf16_f32 v67, v74, v75
	v_cvt_pk_bf16_f32 v68, v68, v69
	v_cvt_pk_bf16_f32 v69, v70, v71
	v_cvt_pk_bf16_f32 v70, v80, v81
	v_cvt_pk_bf16_f32 v71, v88, v89
	global_store_dwordx4 v[86:87], v[64:67], off
	global_store_dwordx4 v[86:87], v[68:71], off offset:256
	s_nop 1
	v_mov_b32_e32 v64, v248
	v_add_u32_e32 v66, 0x90, v146
	v_lshlrev_b64 v[70:71], 11, v[82:83]
	v_lshlrev_b32_e32 v68, 1, v66
	v_lshl_add_u64 v[70:71], s[48:49], 0, v[70:71]
	v_ashrrev_i32_e32 v69, 31, v68
	v_lshl_add_u64 v[70:71], v[70:71], 0, v[148:149]
	v_lshl_add_u64 v[68:69], v[68:69], 2, s[62:63]
	v_ashrrev_i32_e32 v67, 31, v66
	v_pk_mul_f32 v[62:63], v[62:63], v[64:65] op_sel_hi:[1,0]
	v_pk_mul_f32 v[60:61], v[60:61], v[64:65] op_sel_hi:[1,0]
	v_pk_mul_f32 v[58:59], v[58:59], v[64:65] op_sel_hi:[1,0]
	v_pk_mul_f32 v[56:57], v[56:57], v[64:65] op_sel_hi:[1,0]
	v_pk_mul_f32 v[54:55], v[54:55], v[64:65] op_sel_hi:[1,0]
	v_pk_mul_f32 v[52:53], v[52:53], v[64:65] op_sel_hi:[1,0]
	v_pk_mul_f32 v[72:73], v[50:51], v[64:65] op_sel_hi:[1,0]
	v_pk_mul_f32 v[64:65], v[48:49], v[64:65] op_sel_hi:[1,0]
	v_cvt_pk_bf16_f32 v48, v60, v61
	v_cvt_pk_bf16_f32 v49, v62, v63
	v_cvt_pk_bf16_f32 v50, v56, v57
	v_cvt_pk_bf16_f32 v51, v58, v59
	v_cvt_pk_bf16_f32 v52, v52, v53
	v_cvt_pk_bf16_f32 v53, v54, v55
	v_cvt_pk_bf16_f32 v54, v64, v65
	v_cvt_pk_bf16_f32 v55, v72, v73
	global_store_dwordx4 v[70:71], v[48:51], off
	global_store_dwordx4 v[70:71], v[52:55], off offset:256
	s_nop 1
	v_mov_b32_e32 v48, v249
	v_add_u32_e32 v50, 0xa0, v146
	v_lshlrev_b64 v[54:55], 11, v[66:67]
	v_lshlrev_b32_e32 v52, 1, v50
	v_lshl_add_u64 v[54:55], s[48:49], 0, v[54:55]
	v_ashrrev_i32_e32 v53, 31, v52
	v_lshl_add_u64 v[54:55], v[54:55], 0, v[148:149]
	v_lshl_add_u64 v[52:53], v[52:53], 2, s[62:63]
	v_ashrrev_i32_e32 v51, 31, v50
	v_pk_mul_f32 v[46:47], v[46:47], v[48:49] op_sel_hi:[1,0]
	v_pk_mul_f32 v[44:45], v[44:45], v[48:49] op_sel_hi:[1,0]
	v_pk_mul_f32 v[42:43], v[42:43], v[48:49] op_sel_hi:[1,0]
	v_pk_mul_f32 v[40:41], v[40:41], v[48:49] op_sel_hi:[1,0]
	v_pk_mul_f32 v[38:39], v[38:39], v[48:49] op_sel_hi:[1,0]
	v_pk_mul_f32 v[36:37], v[36:37], v[48:49] op_sel_hi:[1,0]
	v_pk_mul_f32 v[56:57], v[34:35], v[48:49] op_sel_hi:[1,0]
	v_pk_mul_f32 v[48:49], v[32:33], v[48:49] op_sel_hi:[1,0]
	v_cvt_pk_bf16_f32 v32, v44, v45
	v_cvt_pk_bf16_f32 v33, v46, v47
	v_cvt_pk_bf16_f32 v34, v40, v41
	v_cvt_pk_bf16_f32 v35, v42, v43
	v_cvt_pk_bf16_f32 v36, v36, v37
	v_cvt_pk_bf16_f32 v37, v38, v39
	v_cvt_pk_bf16_f32 v38, v48, v49
	v_cvt_pk_bf16_f32 v39, v56, v57
	global_store_dwordx4 v[54:55], v[32:35], off
	global_store_dwordx4 v[54:55], v[36:39], off offset:256
	s_nop 1
	v_mov_b32_e32 v32, v250
	v_add_u32_e32 v34, 0xb0, v146
	v_lshlrev_b64 v[38:39], 11, v[50:51]
	v_lshlrev_b32_e32 v36, 1, v34
	v_lshl_add_u64 v[38:39], s[48:49], 0, v[38:39]
	v_ashrrev_i32_e32 v37, 31, v36
	v_lshl_add_u64 v[38:39], v[38:39], 0, v[148:149]
	v_lshl_add_u64 v[36:37], v[36:37], 2, s[62:63]
	v_ashrrev_i32_e32 v35, 31, v34
	v_pk_mul_f32 v[30:31], v[30:31], v[32:33] op_sel_hi:[1,0]
	v_pk_mul_f32 v[28:29], v[28:29], v[32:33] op_sel_hi:[1,0]
	v_pk_mul_f32 v[26:27], v[26:27], v[32:33] op_sel_hi:[1,0]
	v_pk_mul_f32 v[24:25], v[24:25], v[32:33] op_sel_hi:[1,0]
	v_pk_mul_f32 v[22:23], v[22:23], v[32:33] op_sel_hi:[1,0]
	v_pk_mul_f32 v[20:21], v[20:21], v[32:33] op_sel_hi:[1,0]
	v_pk_mul_f32 v[40:41], v[18:19], v[32:33] op_sel_hi:[1,0]
	v_pk_mul_f32 v[32:33], v[16:17], v[32:33] op_sel_hi:[1,0]
	v_cvt_pk_bf16_f32 v16, v28, v29
	v_cvt_pk_bf16_f32 v17, v30, v31
	v_cvt_pk_bf16_f32 v18, v24, v25
	v_cvt_pk_bf16_f32 v19, v26, v27
	v_cvt_pk_bf16_f32 v20, v20, v21
	v_cvt_pk_bf16_f32 v21, v22, v23
	v_cvt_pk_bf16_f32 v22, v32, v33
	v_cvt_pk_bf16_f32 v23, v40, v41
	global_store_dwordx4 v[38:39], v[16:19], off
	global_store_dwordx4 v[38:39], v[20:23], off offset:256
	s_nop 1
	v_mov_b32_e32 v16, v251
	v_lshlrev_b64 v[18:19], 11, v[34:35]
	v_lshl_add_u64 v[18:19], s[48:49], 0, v[18:19]
	v_lshl_add_u64 v[18:19], v[18:19], 0, v[148:149]
	v_pk_mul_f32 v[14:15], v[14:15], v[16:17] op_sel_hi:[1,0]
	v_pk_mul_f32 v[12:13], v[12:13], v[16:17] op_sel_hi:[1,0]
	v_pk_mul_f32 v[10:11], v[10:11], v[16:17] op_sel_hi:[1,0]
	v_pk_mul_f32 v[8:9], v[8:9], v[16:17] op_sel_hi:[1,0]
	v_pk_mul_f32 v[6:7], v[6:7], v[16:17] op_sel_hi:[1,0]
	v_pk_mul_f32 v[4:5], v[4:5], v[16:17] op_sel_hi:[1,0]
	v_pk_mul_f32 v[20:21], v[2:3], v[16:17] op_sel_hi:[1,0]
	v_pk_mul_f32 v[16:17], v[0:1], v[16:17] op_sel_hi:[1,0]
	v_cvt_pk_bf16_f32 v0, v12, v13
	v_cvt_pk_bf16_f32 v1, v14, v15
	v_cvt_pk_bf16_f32 v2, v8, v9
	v_cvt_pk_bf16_f32 v3, v10, v11
	v_cvt_pk_bf16_f32 v4, v4, v5
	v_cvt_pk_bf16_f32 v5, v6, v7
	v_cvt_pk_bf16_f32 v6, v16, v17
	v_cvt_pk_bf16_f32 v7, v20, v21
	global_store_dwordx4 v[18:19], v[0:3], off
	global_store_dwordx4 v[18:19], v[4:7], off offset:256
	s_and_b64 vcc, exec, s[6:7]
	s_mov_b64 s[6:7], -1
	s_cbranch_vccnz .LBB0_1427
